# attention: first QK K-fragment reads hoisted above DMA issue; first 4 PV B-fragments prefetched during softmax
# baseline (speedup 1.0000x reference)
.LBB0_513:
	s_lshl_b32 s4, s76, 14
	s_waitcnt lgkmcnt(7)
	v_mfma_f32_32x32x16_bf16 v[144:159], v[192:195], v[160:163], 0
	s_waitcnt lgkmcnt(6)
	v_mfma_f32_32x32x16_bf16 v[128:143], v[196:199], v[160:163], 0
	v_add3_u32 v236, s4, v225, v220
	ds_read_b128 v[192:195], v236
	ds_read_b128 v[196:199], v236 offset:8192
	s_waitcnt lgkmcnt(7)
	v_mfma_f32_32x32x16_bf16 v[144:159], v[200:203], v[164:167], v[144:159]
	s_waitcnt lgkmcnt(6)
	v_mfma_f32_32x32x16_bf16 v[128:143], v[204:207], v[164:167], v[128:143]
	v_add3_u32 v236, s4, v227, v220
	ds_read_b128 v[200:203], v236
	ds_read_b128 v[204:207], v236 offset:8192
	s_waitcnt lgkmcnt(7)
	v_mfma_f32_32x32x16_bf16 v[144:159], v[240:243], v[168:171], v[144:159]
	s_waitcnt lgkmcnt(6)
	v_mfma_f32_32x32x16_bf16 v[128:143], v[244:247], v[168:171], v[128:143]
	v_add3_u32 v236, s4, v228, v220
	ds_read_b128 v[240:243], v236
	ds_read_b128 v[244:247], v236 offset:8192
	s_waitcnt lgkmcnt(7)
	v_mfma_f32_32x32x16_bf16 v[144:159], v[248:251], v[172:175], v[144:159]
	s_waitcnt lgkmcnt(6)
	v_mfma_f32_32x32x16_bf16 v[128:143], v[252:255], v[172:175], v[128:143]
	v_add3_u32 v236, s4, v229, v220
	ds_read_b128 v[248:251], v236
	ds_read_b128 v[252:255], v236 offset:8192
	s_waitcnt lgkmcnt(7)
	v_mfma_f32_32x32x16_bf16 v[144:159], v[192:195], v[176:179], v[144:159]
	s_waitcnt lgkmcnt(6)
	v_mfma_f32_32x32x16_bf16 v[128:143], v[196:199], v[176:179], v[128:143]
	s_waitcnt lgkmcnt(5)
	v_mfma_f32_32x32x16_bf16 v[144:159], v[200:203], v[180:183], v[144:159]
	s_waitcnt lgkmcnt(4)
	v_mfma_f32_32x32x16_bf16 v[128:143], v[204:207], v[180:183], v[128:143]
	s_waitcnt lgkmcnt(3)
	v_mfma_f32_32x32x16_bf16 v[144:159], v[240:243], v[184:187], v[144:159]
	s_waitcnt lgkmcnt(2)
	v_mfma_f32_32x32x16_bf16 v[128:143], v[244:247], v[184:187], v[128:143]
	s_waitcnt lgkmcnt(1)
	v_mfma_f32_32x32x16_bf16 v[144:159], v[248:251], v[188:191], v[144:159]
	s_waitcnt lgkmcnt(0)
	v_mfma_f32_32x32x16_bf16 v[128:143], v[252:255], v[188:191], v[128:143]
	v_lshl_add_u32 v236, s76, 15, v230
	ds_read_b64_tr_b16 v[240:241], v236 offset:0
	ds_read_b64_tr_b16 v[242:243], v236 offset:4096
	ds_read_b64_tr_b16 v[244:245], v236 offset:8192
	ds_read_b64_tr_b16 v[246:247], v236 offset:12288
	ds_read_b64_tr_b16 v[248:249], v236 offset:16384
	ds_read_b64_tr_b16 v[250:251], v236 offset:20480
	ds_read_b64_tr_b16 v[252:253], v236 offset:24576
	ds_read_b64_tr_b16 v[254:255], v236 offset:28672
	s_nop 9
	v_max_f32_e32 v192, v144, v145
	v_max3_f32 v192, v192, v146, v147
	v_max3_f32 v192, v192, v148, v149
	v_max3_f32 v192, v192, v150, v151
	v_max3_f32 v192, v192, v152, v153
	v_max3_f32 v192, v192, v154, v155
	v_max3_f32 v192, v192, v156, v157
	v_max3_f32 v192, v192, v158, v159
	v_max3_f32 v192, v192, v128, v129
	v_max3_f32 v192, v192, v130, v131
	v_max3_f32 v192, v192, v132, v133
	v_max3_f32 v192, v192, v134, v135
	v_max3_f32 v192, v192, v136, v137
	v_max3_f32 v192, v192, v138, v139
	v_max3_f32 v192, v192, v140, v141
	v_max3_f32 v192, v192, v142, v143
	v_mov_b32_e32 v193, v192
	s_nop 1
	v_permlane32_swap_b32_e32 v192, v193
	v_max_f32_e32 v192, v192, v193
	v_sub_f32_e32 v193, v192, v231
	v_cmp_ge_f32_e32 vcc, s38, v193
	v_max_f32_e32 v234, v231, v192
	v_sub_f32_e32 v192, v231, v234
	v_mul_f32_e32 v192, 0x3e0293ee, v192
	v_exp_f32_e32 v192, v192
	s_cmp_eq_u64 vcc, exec
	s_cselect_b64 s[4:5], -1, 0
	v_cndmask_b32_e64 v233, v192, 1.0, s[4:5]
	v_cmp_gt_f32_e32 vcc, 1.0, v233
	s_cbranch_vccz .LBB0_517
	s_and_saveexec_b64 s[24:25], s[0:1]
	ds_write_b32 v226, v233 offset:128
	s_or_b64 exec, exec, s[24:25]
	s_waitcnt lgkmcnt(0)
	v_add_u32_e32 v192, s21, v210
	ds_read_b128 v[204:207], v192 offset:224
	ds_read_b128 v[200:203], v192 offset:192
	ds_read_b128 v[196:199], v192 offset:160
	ds_read_b128 v[192:195], v192 offset:128
	s_waitcnt lgkmcnt(3)
	v_pk_mul_f32 v[12:13], v[12:13], v[204:205]
	s_waitcnt lgkmcnt(2)
	v_pk_mul_f32 v[8:9], v[8:9], v[200:201]
	s_waitcnt lgkmcnt(1)
	v_pk_mul_f32 v[4:5], v[4:5], v[196:197]
	v_pk_mul_f32 v[14:15], v[14:15], v[206:207]
	v_pk_mul_f32 v[10:11], v[10:11], v[202:203]
	v_pk_mul_f32 v[6:7], v[6:7], v[198:199]
	s_waitcnt lgkmcnt(0)
	v_pk_mul_f32 v[2:3], v[2:3], v[194:195]
	v_pk_mul_f32 v[0:1], v[0:1], v[192:193]
	v_pk_mul_f32 v[124:125], v[124:125], v[204:205]
	v_pk_mul_f32 v[120:121], v[120:121], v[200:201]
	v_pk_mul_f32 v[116:117], v[116:117], v[196:197]
	v_pk_mul_f32 v[126:127], v[126:127], v[206:207]
	v_pk_mul_f32 v[122:123], v[122:123], v[202:203]
	v_pk_mul_f32 v[118:119], v[118:119], v[198:199]
	v_pk_mul_f32 v[114:115], v[114:115], v[194:195]
	v_pk_mul_f32 v[112:113], v[112:113], v[192:193]
	v_pk_mul_f32 v[108:109], v[108:109], v[204:205]
	v_pk_mul_f32 v[104:105], v[104:105], v[200:201]
	v_pk_mul_f32 v[100:101], v[100:101], v[196:197]
	v_pk_mul_f32 v[110:111], v[110:111], v[206:207]
	v_pk_mul_f32 v[106:107], v[106:107], v[202:203]
	v_pk_mul_f32 v[102:103], v[102:103], v[198:199]
	v_pk_mul_f32 v[98:99], v[98:99], v[194:195]
	v_pk_mul_f32 v[96:97], v[96:97], v[192:193]
	v_pk_mul_f32 v[92:93], v[92:93], v[204:205]
	v_pk_mul_f32 v[88:89], v[88:89], v[200:201]
	v_pk_mul_f32 v[84:85], v[84:85], v[196:197]
	v_pk_mul_f32 v[94:95], v[94:95], v[206:207]
	v_pk_mul_f32 v[90:91], v[90:91], v[202:203]
	v_pk_mul_f32 v[86:87], v[86:87], v[198:199]
	v_pk_mul_f32 v[82:83], v[82:83], v[194:195]
	v_pk_mul_f32 v[80:81], v[80:81], v[192:193]
	v_pk_mul_f32 v[76:77], v[76:77], v[204:205]
	v_pk_mul_f32 v[72:73], v[72:73], v[200:201]
	v_pk_mul_f32 v[68:69], v[68:69], v[196:197]
	v_pk_mul_f32 v[78:79], v[78:79], v[206:207]
	v_pk_mul_f32 v[74:75], v[74:75], v[202:203]
	v_pk_mul_f32 v[70:71], v[70:71], v[198:199]
	v_pk_mul_f32 v[66:67], v[66:67], v[194:195]
	v_pk_mul_f32 v[64:65], v[64:65], v[192:193]
	v_pk_mul_f32 v[60:61], v[60:61], v[204:205]
	v_pk_mul_f32 v[56:57], v[56:57], v[200:201]
	v_pk_mul_f32 v[52:53], v[52:53], v[196:197]
	v_pk_mul_f32 v[62:63], v[62:63], v[206:207]
	v_pk_mul_f32 v[58:59], v[58:59], v[202:203]
	v_pk_mul_f32 v[54:55], v[54:55], v[198:199]
	v_pk_mul_f32 v[50:51], v[50:51], v[194:195]
	v_pk_mul_f32 v[48:49], v[48:49], v[192:193]
	v_pk_mul_f32 v[44:45], v[44:45], v[204:205]
	v_pk_mul_f32 v[40:41], v[40:41], v[200:201]
	v_pk_mul_f32 v[36:37], v[36:37], v[196:197]
	v_pk_mul_f32 v[46:47], v[46:47], v[206:207]
	v_pk_mul_f32 v[42:43], v[42:43], v[202:203]
	v_pk_mul_f32 v[38:39], v[38:39], v[198:199]
	v_pk_mul_f32 v[34:35], v[34:35], v[194:195]
	v_pk_mul_f32 v[32:33], v[32:33], v[192:193]
	v_pk_mul_f32 v[28:29], v[28:29], v[204:205]
	v_pk_mul_f32 v[24:25], v[24:25], v[200:201]
	v_pk_mul_f32 v[20:21], v[20:21], v[196:197]
	v_pk_mul_f32 v[30:31], v[30:31], v[206:207]
	v_pk_mul_f32 v[26:27], v[26:27], v[202:203]
	v_pk_mul_f32 v[22:23], v[22:23], v[198:199]
	v_pk_mul_f32 v[18:19], v[18:19], v[194:195]
	v_pk_mul_f32 v[16:17], v[16:17], v[192:193]
.LBB0_517:
	v_cndmask_b32_e64 v231, v234, v231, s[4:5]
	v_mul_f32_e32 v192, 0xbe0293ee, v231
	v_fmamk_f32 v144, v144, 0x3e0293ee, v192
	v_fmamk_f32 v145, v145, 0x3e0293ee, v192
	v_fmamk_f32 v146, v146, 0x3e0293ee, v192
	v_fmamk_f32 v147, v147, 0x3e0293ee, v192
	v_fmamk_f32 v148, v148, 0x3e0293ee, v192
	v_fmamk_f32 v149, v149, 0x3e0293ee, v192
	v_fmamk_f32 v150, v150, 0x3e0293ee, v192
	v_fmamk_f32 v151, v151, 0x3e0293ee, v192
	v_fmamk_f32 v152, v152, 0x3e0293ee, v192
	v_fmamk_f32 v153, v153, 0x3e0293ee, v192
	v_fmamk_f32 v154, v154, 0x3e0293ee, v192
	v_fmamk_f32 v155, v155, 0x3e0293ee, v192
	v_fmamk_f32 v156, v156, 0x3e0293ee, v192
	v_fmamk_f32 v157, v157, 0x3e0293ee, v192
	v_fmamk_f32 v158, v158, 0x3e0293ee, v192
	v_fmamk_f32 v159, v159, 0x3e0293ee, v192
	v_fmamk_f32 v128, v128, 0x3e0293ee, v192
	v_fmamk_f32 v129, v129, 0x3e0293ee, v192
	v_fmamk_f32 v130, v130, 0x3e0293ee, v192
	v_fmamk_f32 v131, v131, 0x3e0293ee, v192
	v_fmamk_f32 v132, v132, 0x3e0293ee, v192
	v_fmamk_f32 v133, v133, 0x3e0293ee, v192
	v_fmamk_f32 v134, v134, 0x3e0293ee, v192
	v_fmamk_f32 v135, v135, 0x3e0293ee, v192
	v_fmamk_f32 v136, v136, 0x3e0293ee, v192
	v_fmamk_f32 v137, v137, 0x3e0293ee, v192
	v_fmamk_f32 v138, v138, 0x3e0293ee, v192
	v_fmamk_f32 v139, v139, 0x3e0293ee, v192
	v_fmamk_f32 v140, v140, 0x3e0293ee, v192
	v_fmamk_f32 v141, v141, 0x3e0293ee, v192
	v_fmamk_f32 v142, v142, 0x3e0293ee, v192
	v_fmac_f32_e32 v192, 0x3e0293ee, v143
	v_exp_f32_e32 v143, v144
	v_exp_f32_e32 v145, v145
	v_exp_f32_e32 v146, v146
	v_exp_f32_e32 v147, v147
	v_exp_f32_e32 v148, v148
	v_exp_f32_e32 v193, v128
	v_exp_f32_e32 v149, v149
	v_add_f32_e32 v128, v145, v143
	v_exp_f32_e32 v150, v150
	v_add_f32_e32 v128, v146, v128
	v_exp_f32_e32 v151, v151
	v_add_f32_e32 v128, v147, v128
	v_exp_f32_e32 v152, v152
	v_add_f32_e32 v128, v148, v128
	v_exp_f32_e32 v153, v153
	v_add_f32_e32 v128, v149, v128
	v_exp_f32_e32 v154, v154
	v_add_f32_e32 v128, v150, v128
	v_exp_f32_e32 v155, v155
	v_add_f32_e32 v128, v151, v128
	v_exp_f32_e32 v156, v156
	v_add_f32_e32 v128, v152, v128
	v_exp_f32_e32 v157, v157
	v_add_f32_e32 v128, v153, v128
	v_exp_f32_e32 v158, v158
	v_add_f32_e32 v128, v154, v128
	v_exp_f32_e32 v159, v159
	v_add_f32_e32 v128, v155, v128
	v_add_f32_e32 v128, v156, v128
	v_exp_f32_e32 v194, v129
	v_add_f32_e32 v128, v157, v128
	v_exp_f32_e32 v195, v130
	v_add_f32_e32 v128, v158, v128
	v_exp_f32_e32 v196, v131
	v_add_f32_e32 v128, v159, v128
	v_exp_f32_e32 v197, v132
	v_add_f32_e32 v128, v193, v128
	v_exp_f32_e32 v198, v133
	v_add_f32_e32 v128, v194, v128
	v_exp_f32_e32 v199, v134
	v_add_f32_e32 v128, v195, v128
	v_exp_f32_e32 v135, v135
	v_add_f32_e32 v128, v196, v128
	v_exp_f32_e32 v200, v136
	v_add_f32_e32 v128, v197, v128
	v_exp_f32_e32 v201, v137
	v_add_f32_e32 v128, v198, v128
	v_exp_f32_e32 v202, v138
	v_add_f32_e32 v128, v199, v128
	v_exp_f32_e32 v203, v139
	v_add_f32_e32 v128, v135, v128
	v_exp_f32_e32 v204, v140
	v_add_f32_e32 v128, v200, v128
	v_exp_f32_e32 v205, v141
	v_add_f32_e32 v128, v201, v128
	v_exp_f32_e32 v206, v142
	v_add_f32_e32 v128, v202, v128
	v_exp_f32_e32 v192, v192
	v_add_f32_e32 v128, v203, v128
	v_add_f32_e32 v128, v204, v128
	v_add_f32_e32 v128, v205, v128
	v_add_f32_e32 v128, v206, v128
	v_add_f32_e32 v128, v192, v128
	v_mov_b32_e32 v129, v128
	s_nop 1
	v_permlane32_swap_b32_e32 v128, v129
	v_add_f32_e32 v144, v128, v129
	v_fmac_f32_e32 v144, v232, v233
	v_cvt_pk_bf16_f32 v128, v143, v145
	v_cvt_pk_bf16_f32 v129, v146, v147
	v_cvt_pk_bf16_f32 v130, v148, v149
	v_cvt_pk_bf16_f32 v131, v150, v151
	v_cvt_pk_bf16_f32 v136, v152, v153
	v_cvt_pk_bf16_f32 v137, v154, v155
	v_cvt_pk_bf16_f32 v138, v156, v157
	v_cvt_pk_bf16_f32 v139, v158, v159
	v_cvt_pk_bf16_f32 v132, v193, v194
	v_cvt_pk_bf16_f32 v133, v195, v196
	v_cvt_pk_bf16_f32 v134, v197, v198
	v_cvt_pk_bf16_f32 v135, v199, v135
	v_cvt_pk_bf16_f32 v140, v200, v201
	v_cvt_pk_bf16_f32 v141, v202, v203
	v_cvt_pk_bf16_f32 v142, v204, v205
	v_cvt_pk_bf16_f32 v143, v206, v192
	v_lshl_add_u32 v145, s76, 15, v230
	ds_read_b64_tr_b16 v[146:147], v145 offset:512
	ds_read_b64_tr_b16 v[148:149], v145 offset:4608
	ds_read_b64_tr_b16 v[150:151], v145 offset:8704
	ds_read_b64_tr_b16 v[152:153], v145 offset:12800
	ds_read_b64_tr_b16 v[154:155], v145 offset:16896
	ds_read_b64_tr_b16 v[156:157], v145 offset:20992
	ds_read_b64_tr_b16 v[192:193], v145 offset:25088
	ds_read_b64_tr_b16 v[194:195], v145 offset:29184
	ds_read_b64_tr_b16 v[196:197], v145 offset:1024
	ds_read_b64_tr_b16 v[198:199], v145 offset:5120
	ds_read_b64_tr_b16 v[200:201], v145 offset:9216
	ds_read_b64_tr_b16 v[202:203], v145 offset:13312
	ds_read_b64_tr_b16 v[204:205], v145 offset:17408
	ds_read_b64_tr_b16 v[206:207], v145 offset:21504
	s_waitcnt lgkmcnt(14)
	s_nop 0
	v_mfma_f32_32x32x16_bf16 v[0:15], v[128:131], v[240:243], v[0:15]
	v_mfma_f32_32x32x16_bf16 v[0:15], v[136:139], v[244:247], v[0:15]
	v_mfma_f32_32x32x16_bf16 v[0:15], v[132:135], v[248:251], v[0:15]
	v_mfma_f32_32x32x16_bf16 v[0:15], v[140:143], v[252:255], v[0:15]
	s_waitcnt lgkmcnt(12)
	v_mfma_f32_32x32x16_bf16 v[112:127], v[128:131], v[146:149], v[112:127]
	ds_read_b64_tr_b16 v[232:233], v145 offset:25600
	ds_read_b64_tr_b16 v[234:235], v145 offset:29696
	s_waitcnt lgkmcnt(12)
	v_mfma_f32_32x32x16_bf16 v[112:127], v[136:139], v[150:153], v[112:127]
	ds_read_b64_tr_b16 v[146:147], v145 offset:1536
	ds_read_b64_tr_b16 v[148:149], v145 offset:5632
	s_waitcnt lgkmcnt(12)
	v_mfma_f32_32x32x16_bf16 v[112:127], v[132:135], v[154:157], v[112:127]
	ds_read_b64_tr_b16 v[150:151], v145 offset:9728
	ds_read_b64_tr_b16 v[152:153], v145 offset:13824
	s_waitcnt lgkmcnt(12)
	v_mfma_f32_32x32x16_bf16 v[112:127], v[140:143], v[192:195], v[112:127]
	ds_read_b64_tr_b16 v[154:155], v145 offset:17920
	ds_read_b64_tr_b16 v[156:157], v145 offset:22016
	s_waitcnt lgkmcnt(12)
	v_mfma_f32_32x32x16_bf16 v[96:111], v[128:131], v[196:199], v[96:111]
	ds_read_b64_tr_b16 v[192:193], v145 offset:26112
	ds_read_b64_tr_b16 v[194:195], v145 offset:30208
	s_waitcnt lgkmcnt(12)
	v_mfma_f32_32x32x16_bf16 v[96:111], v[136:139], v[200:203], v[96:111]
	ds_read_b64_tr_b16 v[196:197], v145 offset:2048
	ds_read_b64_tr_b16 v[198:199], v145 offset:6144
	s_waitcnt lgkmcnt(12)
	v_mfma_f32_32x32x16_bf16 v[96:111], v[132:135], v[204:207], v[96:111]
	ds_read_b64_tr_b16 v[200:201], v145 offset:10240
	ds_read_b64_tr_b16 v[202:203], v145 offset:14336
	s_waitcnt lgkmcnt(12)
	v_mfma_f32_32x32x16_bf16 v[96:111], v[140:143], v[232:235], v[96:111]
	ds_read_b64_tr_b16 v[204:205], v145 offset:18432
	ds_read_b64_tr_b16 v[206:207], v145 offset:22528
	s_waitcnt lgkmcnt(12)
	v_mfma_f32_32x32x16_bf16 v[80:95], v[128:131], v[146:149], v[80:95]
	ds_read_b64_tr_b16 v[232:233], v145 offset:26624
	ds_read_b64_tr_b16 v[234:235], v145 offset:30720
	s_waitcnt lgkmcnt(12)
	v_mfma_f32_32x32x16_bf16 v[80:95], v[136:139], v[150:153], v[80:95]
	ds_read_b64_tr_b16 v[146:147], v145 offset:2560
	ds_read_b64_tr_b16 v[148:149], v145 offset:6656
	s_waitcnt lgkmcnt(12)
	v_mfma_f32_32x32x16_bf16 v[80:95], v[132:135], v[154:157], v[80:95]
	ds_read_b64_tr_b16 v[150:151], v145 offset:10752
	ds_read_b64_tr_b16 v[152:153], v145 offset:14848
	s_waitcnt lgkmcnt(12)
	v_mfma_f32_32x32x16_bf16 v[80:95], v[140:143], v[192:195], v[80:95]
	ds_read_b64_tr_b16 v[154:155], v145 offset:18944
	ds_read_b64_tr_b16 v[156:157], v145 offset:23040
	s_waitcnt lgkmcnt(12)
	v_mfma_f32_32x32x16_bf16 v[64:79], v[128:131], v[196:199], v[64:79]
	ds_read_b64_tr_b16 v[192:193], v145 offset:27136
	ds_read_b64_tr_b16 v[194:195], v145 offset:31232
	s_waitcnt lgkmcnt(12)
	v_mfma_f32_32x32x16_bf16 v[64:79], v[136:139], v[200:203], v[64:79]
	ds_read_b64_tr_b16 v[196:197], v145 offset:3072
	ds_read_b64_tr_b16 v[198:199], v145 offset:7168
	s_waitcnt lgkmcnt(12)
	v_mfma_f32_32x32x16_bf16 v[64:79], v[132:135], v[204:207], v[64:79]
	ds_read_b64_tr_b16 v[200:201], v145 offset:11264
	ds_read_b64_tr_b16 v[202:203], v145 offset:15360
	s_waitcnt lgkmcnt(12)
	v_mfma_f32_32x32x16_bf16 v[64:79], v[140:143], v[232:235], v[64:79]
	ds_read_b64_tr_b16 v[204:205], v145 offset:19456
	ds_read_b64_tr_b16 v[206:207], v145 offset:23552
	s_waitcnt lgkmcnt(12)
	v_mfma_f32_32x32x16_bf16 v[48:63], v[128:131], v[146:149], v[48:63]
	ds_read_b64_tr_b16 v[232:233], v145 offset:27648
	ds_read_b64_tr_b16 v[234:235], v145 offset:31744
	s_waitcnt lgkmcnt(12)
	v_mfma_f32_32x32x16_bf16 v[48:63], v[136:139], v[150:153], v[48:63]
	ds_read_b64_tr_b16 v[146:147], v145 offset:3584
	ds_read_b64_tr_b16 v[148:149], v145 offset:7680
	s_waitcnt lgkmcnt(12)
	v_mfma_f32_32x32x16_bf16 v[48:63], v[132:135], v[154:157], v[48:63]
	ds_read_b64_tr_b16 v[150:151], v145 offset:11776
	ds_read_b64_tr_b16 v[152:153], v145 offset:15872
	s_waitcnt lgkmcnt(12)
	v_mfma_f32_32x32x16_bf16 v[48:63], v[140:143], v[192:195], v[48:63]
	ds_read_b64_tr_b16 v[154:155], v145 offset:19968
	ds_read_b64_tr_b16 v[156:157], v145 offset:24064
	s_waitcnt lgkmcnt(12)
	v_mfma_f32_32x32x16_bf16 v[32:47], v[128:131], v[196:199], v[32:47]
	ds_read_b64_tr_b16 v[192:193], v145 offset:28160
	ds_read_b64_tr_b16 v[194:195], v145 offset:32256
	s_waitcnt lgkmcnt(12)
	v_mfma_f32_32x32x16_bf16 v[32:47], v[136:139], v[200:203], v[32:47]
	s_waitcnt lgkmcnt(10)
	v_mfma_f32_32x32x16_bf16 v[32:47], v[132:135], v[204:207], v[32:47]
	s_waitcnt lgkmcnt(8)
	v_mfma_f32_32x32x16_bf16 v[32:47], v[140:143], v[232:235], v[32:47]
	s_waitcnt lgkmcnt(6)
	v_mfma_f32_32x32x16_bf16 v[16:31], v[128:131], v[146:149], v[16:31]
	s_add_i32 s4, s76, 1
	s_cmp_lg_u32 s76, 2
	s_cselect_b32 s76, s4, 0
	s_add_i32 s4, s74, 1
	s_cmp_lg_u32 s74, 2
	s_cselect_b32 s74, s4, 0
	s_add_u32 s22, s22, 0x20000
	s_waitcnt lgkmcnt(4)
	v_mfma_f32_32x32x16_bf16 v[16:31], v[136:139], v[150:153], v[16:31]
	s_addc_u32 s23, s23, 0
	s_add_i32 s86, s86, 1
	s_cmp_eq_u32 s22, 0x800000
	s_waitcnt lgkmcnt(2)
	v_mfma_f32_32x32x16_bf16 v[16:31], v[132:135], v[154:157], v[16:31]
	s_waitcnt lgkmcnt(0)
	v_mfma_f32_32x32x16_bf16 v[16:31], v[140:143], v[192:195], v[16:31]
	s_cbranch_scc1 .LBB0_521
	v_mov_b32_e32 v232, v144
	s_cmp_eq_u32 s22, 0x7e0000
	s_mov_b64 s[4:5], -1
	s_cbranch_scc1 .LBB0_510
.LBB0_519:
	s_waitcnt vmcnt(6) lgkmcnt(0)
	s_barrier
	s_lshl_b32 s4, s76, 14
	v_add3_u32 v236, s4, v221, v220
	ds_read_b128 v[192:195], v236
	ds_read_b128 v[196:199], v236 offset:8192
	v_add3_u32 v236, s4, v222, v220
	ds_read_b128 v[200:203], v236
	ds_read_b128 v[204:207], v236 offset:8192
	v_add3_u32 v236, s4, v223, v220
	ds_read_b128 v[240:243], v236
	ds_read_b128 v[244:247], v236 offset:8192
	v_add3_u32 v236, s4, v224, v220
	ds_read_b128 v[248:251], v236
	ds_read_b128 v[252:255], v236 offset:8192
	s_cbranch_execnz .LBB0_511
.LBB0_520:
	s_waitcnt vmcnt(0) lgkmcnt(0)
	s_barrier
	s_lshl_b32 s4, s76, 14
	v_add3_u32 v236, s4, v221, v220
	ds_read_b128 v[192:195], v236
	ds_read_b128 v[196:199], v236 offset:8192
	v_add3_u32 v236, s4, v222, v220
	ds_read_b128 v[200:203], v236
	ds_read_b128 v[204:207], v236 offset:8192
	v_add3_u32 v236, s4, v223, v220
	ds_read_b128 v[240:243], v236
	ds_read_b128 v[244:247], v236 offset:8192
	v_add3_u32 v236, s4, v224, v220
	ds_read_b128 v[248:251], v236
	ds_read_b128 v[252:255], v236 offset:8192
	s_cmp_gt_u32 s86, 61
	s_cbranch_scc0 .LBB0_512
	s_branch .LBB0_513

.LBB0_906:
	s_lshl_b32 s4, s80, 14
	s_waitcnt lgkmcnt(7)
	v_mfma_f32_32x32x16_bf16 v[144:159], v[192:195], v[160:163], 0
	s_waitcnt lgkmcnt(6)
	v_mfma_f32_32x32x16_bf16 v[128:143], v[196:199], v[160:163], 0
	v_add3_u32 v236, s4, v226, v220
	ds_read_b128 v[192:195], v236
	ds_read_b128 v[196:199], v236 offset:8192
	s_waitcnt lgkmcnt(7)
	v_mfma_f32_32x32x16_bf16 v[144:159], v[200:203], v[164:167], v[144:159]
	s_waitcnt lgkmcnt(6)
	v_mfma_f32_32x32x16_bf16 v[128:143], v[204:207], v[164:167], v[128:143]
	v_add3_u32 v236, s4, v227, v220
	ds_read_b128 v[200:203], v236
	ds_read_b128 v[204:207], v236 offset:8192
	s_waitcnt lgkmcnt(7)
	v_mfma_f32_32x32x16_bf16 v[144:159], v[240:243], v[168:171], v[144:159]
	s_waitcnt lgkmcnt(6)
	v_mfma_f32_32x32x16_bf16 v[128:143], v[244:247], v[168:171], v[128:143]
	v_add3_u32 v236, s4, v228, v220
	ds_read_b128 v[240:243], v236
	ds_read_b128 v[244:247], v236 offset:8192
	s_waitcnt lgkmcnt(7)
	v_mfma_f32_32x32x16_bf16 v[144:159], v[248:251], v[172:175], v[144:159]
	s_waitcnt lgkmcnt(6)
	v_mfma_f32_32x32x16_bf16 v[128:143], v[252:255], v[172:175], v[128:143]
	v_add3_u32 v236, s4, v229, v220
	ds_read_b128 v[248:251], v236
	ds_read_b128 v[252:255], v236 offset:8192
	s_waitcnt lgkmcnt(7)
	v_mfma_f32_32x32x16_bf16 v[144:159], v[192:195], v[176:179], v[144:159]
	s_waitcnt lgkmcnt(6)
	v_mfma_f32_32x32x16_bf16 v[128:143], v[196:199], v[176:179], v[128:143]
	s_waitcnt lgkmcnt(5)
	v_mfma_f32_32x32x16_bf16 v[144:159], v[200:203], v[180:183], v[144:159]
	s_waitcnt lgkmcnt(4)
	v_mfma_f32_32x32x16_bf16 v[128:143], v[204:207], v[180:183], v[128:143]
	s_waitcnt lgkmcnt(3)
	v_mfma_f32_32x32x16_bf16 v[144:159], v[240:243], v[184:187], v[144:159]
	s_waitcnt lgkmcnt(2)
	v_mfma_f32_32x32x16_bf16 v[128:143], v[244:247], v[184:187], v[128:143]
	s_waitcnt lgkmcnt(1)
	v_mfma_f32_32x32x16_bf16 v[144:159], v[248:251], v[188:191], v[144:159]
	s_waitcnt lgkmcnt(0)
	v_mfma_f32_32x32x16_bf16 v[128:143], v[252:255], v[188:191], v[128:143]
	v_lshl_add_u32 v236, s80, 15, v230
	ds_read_b64_tr_b16 v[240:241], v236 offset:0
	ds_read_b64_tr_b16 v[242:243], v236 offset:4096
	ds_read_b64_tr_b16 v[244:245], v236 offset:8192
	ds_read_b64_tr_b16 v[246:247], v236 offset:12288
	ds_read_b64_tr_b16 v[248:249], v236 offset:16384
	ds_read_b64_tr_b16 v[250:251], v236 offset:20480
	ds_read_b64_tr_b16 v[252:253], v236 offset:24576
	ds_read_b64_tr_b16 v[254:255], v236 offset:28672
	v_max_f32_e32 v194, v231, v231
	s_nop 9
	v_max_f32_e32 v192, v144, v145
	v_max3_f32 v192, v192, v146, v147
	v_max3_f32 v192, v192, v148, v149
	v_max3_f32 v192, v192, v150, v151
	v_max3_f32 v192, v192, v152, v153
	v_max3_f32 v192, v192, v154, v155
	v_max3_f32 v192, v192, v156, v157
	v_max3_f32 v192, v192, v158, v159
	v_max3_f32 v192, v192, v128, v129
	v_max3_f32 v192, v192, v130, v131
	v_max3_f32 v192, v192, v132, v133
	v_max3_f32 v192, v192, v134, v135
	v_max3_f32 v192, v192, v136, v137
	v_max3_f32 v192, v192, v138, v139
	v_max3_f32 v192, v192, v140, v141
	v_max3_f32 v192, v192, v142, v143
	v_mov_b32_e32 v193, v192
	s_nop 1
	v_permlane32_swap_b32_e32 v192, v193
	v_max_f32_e32 v192, v192, v193
	v_max_f32_e32 v234, v194, v192
	v_sub_f32_e32 v193, v192, v231
	v_sub_f32_e32 v192, v231, v234
	v_mul_f32_e32 v192, 0x3e0293ee, v192
	v_exp_f32_e32 v192, v192
	v_cmp_ge_f32_e32 vcc, s42, v193
	s_cmp_eq_u64 vcc, exec
	s_cselect_b64 s[4:5], -1, 0
	v_cndmask_b32_e64 v233, v192, 1.0, s[4:5]
	v_cmp_gt_f32_e32 vcc, 1.0, v233
	s_cbranch_vccz .LBB0_910
	s_and_saveexec_b64 s[24:25], s[0:1]
	ds_write_b32 v224, v233 offset:128
	s_or_b64 exec, exec, s[24:25]
	s_waitcnt lgkmcnt(0)
	v_add_u32_e32 v192, s21, v210
	ds_read_b128 v[204:207], v192 offset:224
	ds_read_b128 v[200:203], v192 offset:192
	ds_read_b128 v[196:199], v192 offset:160
	ds_read_b128 v[192:195], v192 offset:128
	s_waitcnt lgkmcnt(3)
	v_pk_mul_f32 v[12:13], v[12:13], v[204:205]
	s_waitcnt lgkmcnt(2)
	v_pk_mul_f32 v[8:9], v[8:9], v[200:201]
	s_waitcnt lgkmcnt(1)
	v_pk_mul_f32 v[4:5], v[4:5], v[196:197]
	v_pk_mul_f32 v[14:15], v[14:15], v[206:207]
	v_pk_mul_f32 v[10:11], v[10:11], v[202:203]
	v_pk_mul_f32 v[6:7], v[6:7], v[198:199]
	s_waitcnt lgkmcnt(0)
	v_pk_mul_f32 v[2:3], v[2:3], v[194:195]
	v_pk_mul_f32 v[0:1], v[0:1], v[192:193]
	v_pk_mul_f32 v[124:125], v[124:125], v[204:205]
	v_pk_mul_f32 v[120:121], v[120:121], v[200:201]
	v_pk_mul_f32 v[116:117], v[116:117], v[196:197]
	v_pk_mul_f32 v[126:127], v[126:127], v[206:207]
	v_pk_mul_f32 v[122:123], v[122:123], v[202:203]
	v_pk_mul_f32 v[118:119], v[118:119], v[198:199]
	v_pk_mul_f32 v[114:115], v[114:115], v[194:195]
	v_pk_mul_f32 v[112:113], v[112:113], v[192:193]
	v_pk_mul_f32 v[108:109], v[108:109], v[204:205]
	v_pk_mul_f32 v[104:105], v[104:105], v[200:201]
	v_pk_mul_f32 v[100:101], v[100:101], v[196:197]
	v_pk_mul_f32 v[110:111], v[110:111], v[206:207]
	v_pk_mul_f32 v[106:107], v[106:107], v[202:203]
	v_pk_mul_f32 v[102:103], v[102:103], v[198:199]
	v_pk_mul_f32 v[98:99], v[98:99], v[194:195]
	v_pk_mul_f32 v[96:97], v[96:97], v[192:193]
	v_pk_mul_f32 v[92:93], v[92:93], v[204:205]
	v_pk_mul_f32 v[88:89], v[88:89], v[200:201]
	v_pk_mul_f32 v[84:85], v[84:85], v[196:197]
	v_pk_mul_f32 v[94:95], v[94:95], v[206:207]
	v_pk_mul_f32 v[90:91], v[90:91], v[202:203]
	v_pk_mul_f32 v[86:87], v[86:87], v[198:199]
	v_pk_mul_f32 v[82:83], v[82:83], v[194:195]
	v_pk_mul_f32 v[80:81], v[80:81], v[192:193]
	v_pk_mul_f32 v[76:77], v[76:77], v[204:205]
	v_pk_mul_f32 v[72:73], v[72:73], v[200:201]
	v_pk_mul_f32 v[68:69], v[68:69], v[196:197]
	v_pk_mul_f32 v[78:79], v[78:79], v[206:207]
	v_pk_mul_f32 v[74:75], v[74:75], v[202:203]
	v_pk_mul_f32 v[70:71], v[70:71], v[198:199]
	v_pk_mul_f32 v[66:67], v[66:67], v[194:195]
	v_pk_mul_f32 v[64:65], v[64:65], v[192:193]
	v_pk_mul_f32 v[60:61], v[60:61], v[204:205]
	v_pk_mul_f32 v[56:57], v[56:57], v[200:201]
	v_pk_mul_f32 v[52:53], v[52:53], v[196:197]
	v_pk_mul_f32 v[62:63], v[62:63], v[206:207]
	v_pk_mul_f32 v[58:59], v[58:59], v[202:203]
	v_pk_mul_f32 v[54:55], v[54:55], v[198:199]
	v_pk_mul_f32 v[50:51], v[50:51], v[194:195]
	v_pk_mul_f32 v[48:49], v[48:49], v[192:193]
	v_pk_mul_f32 v[44:45], v[44:45], v[204:205]
	v_pk_mul_f32 v[40:41], v[40:41], v[200:201]
	v_pk_mul_f32 v[36:37], v[36:37], v[196:197]
	v_pk_mul_f32 v[46:47], v[46:47], v[206:207]
	v_pk_mul_f32 v[42:43], v[42:43], v[202:203]
	v_pk_mul_f32 v[38:39], v[38:39], v[198:199]
	v_pk_mul_f32 v[34:35], v[34:35], v[194:195]
	v_pk_mul_f32 v[32:33], v[32:33], v[192:193]
	v_pk_mul_f32 v[28:29], v[28:29], v[204:205]
	v_pk_mul_f32 v[24:25], v[24:25], v[200:201]
	v_pk_mul_f32 v[20:21], v[20:21], v[196:197]
	v_pk_mul_f32 v[30:31], v[30:31], v[206:207]
	v_pk_mul_f32 v[26:27], v[26:27], v[202:203]
	v_pk_mul_f32 v[22:23], v[22:23], v[198:199]
	v_pk_mul_f32 v[18:19], v[18:19], v[194:195]
	v_pk_mul_f32 v[16:17], v[16:17], v[192:193]
.LBB0_910:
	v_cndmask_b32_e64 v231, v234, v231, s[4:5]
	v_mul_f32_e32 v192, 0xbe0293ee, v231
	v_fmamk_f32 v144, v144, 0x3e0293ee, v192
	v_fmamk_f32 v145, v145, 0x3e0293ee, v192
	v_fmamk_f32 v146, v146, 0x3e0293ee, v192
	v_fmamk_f32 v147, v147, 0x3e0293ee, v192
	v_fmamk_f32 v148, v148, 0x3e0293ee, v192
	v_fmamk_f32 v149, v149, 0x3e0293ee, v192
	v_fmamk_f32 v150, v150, 0x3e0293ee, v192
	v_fmamk_f32 v151, v151, 0x3e0293ee, v192
	v_fmamk_f32 v152, v152, 0x3e0293ee, v192
	v_fmamk_f32 v153, v153, 0x3e0293ee, v192
	v_fmamk_f32 v154, v154, 0x3e0293ee, v192
	v_fmamk_f32 v155, v155, 0x3e0293ee, v192
	v_fmamk_f32 v156, v156, 0x3e0293ee, v192
	v_fmamk_f32 v157, v157, 0x3e0293ee, v192
	v_fmamk_f32 v158, v158, 0x3e0293ee, v192
	v_fmamk_f32 v159, v159, 0x3e0293ee, v192
	v_fmamk_f32 v128, v128, 0x3e0293ee, v192
	v_fmamk_f32 v129, v129, 0x3e0293ee, v192
	v_fmamk_f32 v130, v130, 0x3e0293ee, v192
	v_fmamk_f32 v131, v131, 0x3e0293ee, v192
	v_fmamk_f32 v132, v132, 0x3e0293ee, v192
	v_fmamk_f32 v133, v133, 0x3e0293ee, v192
	v_fmamk_f32 v134, v134, 0x3e0293ee, v192
	v_fmamk_f32 v135, v135, 0x3e0293ee, v192
	v_fmamk_f32 v136, v136, 0x3e0293ee, v192
	v_fmamk_f32 v137, v137, 0x3e0293ee, v192
	v_fmamk_f32 v138, v138, 0x3e0293ee, v192
	v_fmamk_f32 v139, v139, 0x3e0293ee, v192
	v_fmamk_f32 v140, v140, 0x3e0293ee, v192
	v_fmamk_f32 v141, v141, 0x3e0293ee, v192
	v_fmamk_f32 v142, v142, 0x3e0293ee, v192
	v_fmac_f32_e32 v192, 0x3e0293ee, v143
	v_exp_f32_e32 v143, v144
	v_exp_f32_e32 v145, v145
	v_exp_f32_e32 v146, v146
	v_exp_f32_e32 v147, v147
	v_exp_f32_e32 v148, v148
	v_exp_f32_e32 v193, v128
	v_exp_f32_e32 v149, v149
	v_add_f32_e32 v128, v145, v143
	v_exp_f32_e32 v150, v150
	v_add_f32_e32 v128, v146, v128
	v_exp_f32_e32 v151, v151
	v_add_f32_e32 v128, v147, v128
	v_exp_f32_e32 v152, v152
	v_add_f32_e32 v128, v148, v128
	v_exp_f32_e32 v153, v153
	v_add_f32_e32 v128, v149, v128
	v_exp_f32_e32 v154, v154
	v_add_f32_e32 v128, v150, v128
	v_exp_f32_e32 v155, v155
	v_add_f32_e32 v128, v151, v128
	v_exp_f32_e32 v156, v156
	v_add_f32_e32 v128, v152, v128
	v_exp_f32_e32 v157, v157
	v_add_f32_e32 v128, v153, v128
	v_exp_f32_e32 v158, v158
	v_add_f32_e32 v128, v154, v128
	v_exp_f32_e32 v159, v159
	v_add_f32_e32 v128, v155, v128
	v_add_f32_e32 v128, v156, v128
	v_exp_f32_e32 v194, v129
	v_add_f32_e32 v128, v157, v128
	v_exp_f32_e32 v195, v130
	v_add_f32_e32 v128, v158, v128
	v_exp_f32_e32 v196, v131
	v_add_f32_e32 v128, v159, v128
	v_exp_f32_e32 v197, v132
	v_add_f32_e32 v128, v193, v128
	v_exp_f32_e32 v198, v133
	v_add_f32_e32 v128, v194, v128
	v_exp_f32_e32 v199, v134
	v_add_f32_e32 v128, v195, v128
	v_exp_f32_e32 v135, v135
	v_add_f32_e32 v128, v196, v128
	v_exp_f32_e32 v200, v136
	v_add_f32_e32 v128, v197, v128
	v_exp_f32_e32 v201, v137
	v_add_f32_e32 v128, v198, v128
	v_exp_f32_e32 v202, v138
	v_add_f32_e32 v128, v199, v128
	v_exp_f32_e32 v203, v139
	v_add_f32_e32 v128, v135, v128
	v_exp_f32_e32 v204, v140
	v_add_f32_e32 v128, v200, v128
	v_exp_f32_e32 v205, v141
	v_add_f32_e32 v128, v201, v128
	v_exp_f32_e32 v206, v142
	v_add_f32_e32 v128, v202, v128
	v_exp_f32_e32 v192, v192
	v_add_f32_e32 v128, v203, v128
	v_add_f32_e32 v128, v204, v128
	v_add_f32_e32 v128, v205, v128
	v_add_f32_e32 v128, v206, v128
	v_add_f32_e32 v128, v192, v128
	v_mov_b32_e32 v129, v128
	s_nop 1
	v_permlane32_swap_b32_e32 v128, v129
	v_add_f32_e32 v144, v128, v129
	v_fmac_f32_e32 v144, v232, v233
	v_cvt_pk_bf16_f32 v128, v143, v145
	v_cvt_pk_bf16_f32 v129, v146, v147
	v_cvt_pk_bf16_f32 v130, v148, v149
	v_cvt_pk_bf16_f32 v131, v150, v151
	v_cvt_pk_bf16_f32 v136, v152, v153
	v_cvt_pk_bf16_f32 v137, v154, v155
	v_cvt_pk_bf16_f32 v138, v156, v157
	v_cvt_pk_bf16_f32 v139, v158, v159
	v_cvt_pk_bf16_f32 v132, v193, v194
	v_cvt_pk_bf16_f32 v133, v195, v196
	v_cvt_pk_bf16_f32 v134, v197, v198
	v_cvt_pk_bf16_f32 v135, v199, v135
	v_cvt_pk_bf16_f32 v140, v200, v201
	v_cvt_pk_bf16_f32 v141, v202, v203
	v_cvt_pk_bf16_f32 v142, v204, v205
	v_cvt_pk_bf16_f32 v143, v206, v192
	v_lshl_add_u32 v145, s80, 15, v230
	ds_read_b64_tr_b16 v[146:147], v145 offset:512
	ds_read_b64_tr_b16 v[148:149], v145 offset:4608
	ds_read_b64_tr_b16 v[150:151], v145 offset:8704
	ds_read_b64_tr_b16 v[152:153], v145 offset:12800
	ds_read_b64_tr_b16 v[154:155], v145 offset:16896
	ds_read_b64_tr_b16 v[156:157], v145 offset:20992
	ds_read_b64_tr_b16 v[192:193], v145 offset:25088
	ds_read_b64_tr_b16 v[194:195], v145 offset:29184
	ds_read_b64_tr_b16 v[196:197], v145 offset:1024
	ds_read_b64_tr_b16 v[198:199], v145 offset:5120
	ds_read_b64_tr_b16 v[200:201], v145 offset:9216
	ds_read_b64_tr_b16 v[202:203], v145 offset:13312
	ds_read_b64_tr_b16 v[204:205], v145 offset:17408
	ds_read_b64_tr_b16 v[206:207], v145 offset:21504
	s_waitcnt lgkmcnt(14)
	s_nop 0
	v_mfma_f32_32x32x16_bf16 v[0:15], v[128:131], v[240:243], v[0:15]
	v_mfma_f32_32x32x16_bf16 v[0:15], v[136:139], v[244:247], v[0:15]
	v_mfma_f32_32x32x16_bf16 v[0:15], v[132:135], v[248:251], v[0:15]
	v_mfma_f32_32x32x16_bf16 v[0:15], v[140:143], v[252:255], v[0:15]
	s_waitcnt lgkmcnt(12)
	v_mfma_f32_32x32x16_bf16 v[112:127], v[128:131], v[146:149], v[112:127]
	ds_read_b64_tr_b16 v[232:233], v145 offset:25600
	ds_read_b64_tr_b16 v[234:235], v145 offset:29696
	s_waitcnt lgkmcnt(12)
	v_mfma_f32_32x32x16_bf16 v[112:127], v[136:139], v[150:153], v[112:127]
	ds_read_b64_tr_b16 v[146:147], v145 offset:1536
	ds_read_b64_tr_b16 v[148:149], v145 offset:5632
	s_waitcnt lgkmcnt(12)
	v_mfma_f32_32x32x16_bf16 v[112:127], v[132:135], v[154:157], v[112:127]
	ds_read_b64_tr_b16 v[150:151], v145 offset:9728
	ds_read_b64_tr_b16 v[152:153], v145 offset:13824
	s_waitcnt lgkmcnt(12)
	v_mfma_f32_32x32x16_bf16 v[112:127], v[140:143], v[192:195], v[112:127]
	ds_read_b64_tr_b16 v[154:155], v145 offset:17920
	ds_read_b64_tr_b16 v[156:157], v145 offset:22016
	s_waitcnt lgkmcnt(12)
	v_mfma_f32_32x32x16_bf16 v[96:111], v[128:131], v[196:199], v[96:111]
	ds_read_b64_tr_b16 v[192:193], v145 offset:26112
	ds_read_b64_tr_b16 v[194:195], v145 offset:30208
	s_waitcnt lgkmcnt(12)
	v_mfma_f32_32x32x16_bf16 v[96:111], v[136:139], v[200:203], v[96:111]
	ds_read_b64_tr_b16 v[196:197], v145 offset:2048
	ds_read_b64_tr_b16 v[198:199], v145 offset:6144
	s_waitcnt lgkmcnt(12)
	v_mfma_f32_32x32x16_bf16 v[96:111], v[132:135], v[204:207], v[96:111]
	ds_read_b64_tr_b16 v[200:201], v145 offset:10240
	ds_read_b64_tr_b16 v[202:203], v145 offset:14336
	s_waitcnt lgkmcnt(12)
	v_mfma_f32_32x32x16_bf16 v[96:111], v[140:143], v[232:235], v[96:111]
	ds_read_b64_tr_b16 v[204:205], v145 offset:18432
	ds_read_b64_tr_b16 v[206:207], v145 offset:22528
	s_waitcnt lgkmcnt(12)
	v_mfma_f32_32x32x16_bf16 v[80:95], v[128:131], v[146:149], v[80:95]
	ds_read_b64_tr_b16 v[232:233], v145 offset:26624
	ds_read_b64_tr_b16 v[234:235], v145 offset:30720
	s_waitcnt lgkmcnt(12)
	v_mfma_f32_32x32x16_bf16 v[80:95], v[136:139], v[150:153], v[80:95]
	ds_read_b64_tr_b16 v[146:147], v145 offset:2560
	ds_read_b64_tr_b16 v[148:149], v145 offset:6656
	s_waitcnt lgkmcnt(12)
	v_mfma_f32_32x32x16_bf16 v[80:95], v[132:135], v[154:157], v[80:95]
	ds_read_b64_tr_b16 v[150:151], v145 offset:10752
	ds_read_b64_tr_b16 v[152:153], v145 offset:14848
	s_waitcnt lgkmcnt(12)
	v_mfma_f32_32x32x16_bf16 v[80:95], v[140:143], v[192:195], v[80:95]
	ds_read_b64_tr_b16 v[154:155], v145 offset:18944
	ds_read_b64_tr_b16 v[156:157], v145 offset:23040
	s_waitcnt lgkmcnt(12)
	v_mfma_f32_32x32x16_bf16 v[64:79], v[128:131], v[196:199], v[64:79]
	ds_read_b64_tr_b16 v[192:193], v145 offset:27136
	ds_read_b64_tr_b16 v[194:195], v145 offset:31232
	s_waitcnt lgkmcnt(12)
	v_mfma_f32_32x32x16_bf16 v[64:79], v[136:139], v[200:203], v[64:79]
	ds_read_b64_tr_b16 v[196:197], v145 offset:3072
	ds_read_b64_tr_b16 v[198:199], v145 offset:7168
	s_waitcnt lgkmcnt(12)
	v_mfma_f32_32x32x16_bf16 v[64:79], v[132:135], v[204:207], v[64:79]
	ds_read_b64_tr_b16 v[200:201], v145 offset:11264
	ds_read_b64_tr_b16 v[202:203], v145 offset:15360
	s_waitcnt lgkmcnt(12)
	v_mfma_f32_32x32x16_bf16 v[64:79], v[140:143], v[232:235], v[64:79]
	ds_read_b64_tr_b16 v[204:205], v145 offset:19456
	ds_read_b64_tr_b16 v[206:207], v145 offset:23552
	s_waitcnt lgkmcnt(12)
	v_mfma_f32_32x32x16_bf16 v[48:63], v[128:131], v[146:149], v[48:63]
	ds_read_b64_tr_b16 v[232:233], v145 offset:27648
	ds_read_b64_tr_b16 v[234:235], v145 offset:31744
	s_waitcnt lgkmcnt(12)
	v_mfma_f32_32x32x16_bf16 v[48:63], v[136:139], v[150:153], v[48:63]
	ds_read_b64_tr_b16 v[146:147], v145 offset:3584
	ds_read_b64_tr_b16 v[148:149], v145 offset:7680
	s_waitcnt lgkmcnt(12)
	v_mfma_f32_32x32x16_bf16 v[48:63], v[132:135], v[154:157], v[48:63]
	ds_read_b64_tr_b16 v[150:151], v145 offset:11776
	ds_read_b64_tr_b16 v[152:153], v145 offset:15872
	s_waitcnt lgkmcnt(12)
	v_mfma_f32_32x32x16_bf16 v[48:63], v[140:143], v[192:195], v[48:63]
	ds_read_b64_tr_b16 v[154:155], v145 offset:19968
	ds_read_b64_tr_b16 v[156:157], v145 offset:24064
	s_waitcnt lgkmcnt(12)
	v_mfma_f32_32x32x16_bf16 v[32:47], v[128:131], v[196:199], v[32:47]
	ds_read_b64_tr_b16 v[192:193], v145 offset:28160
	ds_read_b64_tr_b16 v[194:195], v145 offset:32256
	s_waitcnt lgkmcnt(12)
	v_mfma_f32_32x32x16_bf16 v[32:47], v[136:139], v[200:203], v[32:47]
	s_waitcnt lgkmcnt(10)
	v_mfma_f32_32x32x16_bf16 v[32:47], v[132:135], v[204:207], v[32:47]
	s_waitcnt lgkmcnt(8)
	v_mfma_f32_32x32x16_bf16 v[32:47], v[140:143], v[232:235], v[32:47]
	s_waitcnt lgkmcnt(6)
	v_mfma_f32_32x32x16_bf16 v[16:31], v[128:131], v[146:149], v[16:31]
	s_add_i32 s4, s80, 1
	s_cmp_lg_u32 s80, 2
	s_cselect_b32 s80, s4, 0
	s_add_i32 s4, s78, 1
	s_cmp_lg_u32 s78, 2
	s_cselect_b32 s78, s4, 0
	s_add_u32 s22, s22, 0x20000
	s_waitcnt lgkmcnt(4)
	v_mfma_f32_32x32x16_bf16 v[16:31], v[136:139], v[150:153], v[16:31]
	s_addc_u32 s23, s23, 0
	s_add_i32 s86, s86, 1
	s_cmp_eq_u32 s22, 0x800000
	s_waitcnt lgkmcnt(2)
	v_mfma_f32_32x32x16_bf16 v[16:31], v[132:135], v[154:157], v[16:31]
	s_waitcnt lgkmcnt(0)
	v_mfma_f32_32x32x16_bf16 v[16:31], v[140:143], v[192:195], v[16:31]
	s_cbranch_scc1 .LBB0_914
	v_mov_b32_e32 v232, v144
	s_cmp_eq_u32 s22, 0x7e0000
	s_mov_b64 s[4:5], -1
	s_cbranch_scc1 .LBB0_903
.LBB0_912:
	s_waitcnt vmcnt(6) lgkmcnt(0)
	s_barrier
	s_lshl_b32 s4, s80, 14
	v_add3_u32 v236, s4, v221, v220
	ds_read_b128 v[192:195], v236
	ds_read_b128 v[196:199], v236 offset:8192
	v_add3_u32 v236, s4, v222, v220
	ds_read_b128 v[200:203], v236
	ds_read_b128 v[204:207], v236 offset:8192
	v_add3_u32 v236, s4, v223, v220
	ds_read_b128 v[240:243], v236
	ds_read_b128 v[244:247], v236 offset:8192
	v_add3_u32 v236, s4, v225, v220
	ds_read_b128 v[248:251], v236
	ds_read_b128 v[252:255], v236 offset:8192
	s_cbranch_execnz .LBB0_904
.LBB0_913:
	s_waitcnt vmcnt(0) lgkmcnt(0)
	s_barrier
	s_lshl_b32 s4, s80, 14
	v_add3_u32 v236, s4, v221, v220
	ds_read_b128 v[192:195], v236
	ds_read_b128 v[196:199], v236 offset:8192
	v_add3_u32 v236, s4, v222, v220
	ds_read_b128 v[200:203], v236
	ds_read_b128 v[204:207], v236 offset:8192
	v_add3_u32 v236, s4, v223, v220
	ds_read_b128 v[240:243], v236
	ds_read_b128 v[244:247], v236 offset:8192
	v_add3_u32 v236, s4, v225, v220
	ds_read_b128 v[248:251], v236
	ds_read_b128 v[252:255], v236 offset:8192
	s_cmp_gt_u32 s86, 61
	s_cbranch_scc0 .LBB0_905
	s_branch .LBB0_906
